# bnorm phase: per-head reduction via DPP moves (quad_perm, row_half_mirror, row_mirror) instead of 16 ds_bpermute round trips per iteration; bit-identical sums
# speedup vs baseline: 1.0031x; 1.0031x over previous
; __device__ __forceinline__ float bf2f(u16 h) { return __uint_as_float(((unsigned)h) << 16); }
; __device__ __forceinline__ float siluf_(float x) { return x * __builtin_amdgcn_rcpf(1.f + __expf(-x)); }
; __device__ void phase_bnorm(const Params& p, int l, int wv) {
;     ...
;     for (int k = 0; k < 4; ++k) {
;       int gidx = g0 + k * gstride;
;       float o0 = __uint_as_float(av[k].x << 16) + __uint_as_float(bv[k].x << 16);
;       float o1 = __uint_as_float(av[k].x & 0xffff0000u) + __uint_as_float(bv[k].x & 0xffff0000u);
;       float o2 = __uint_as_float(av[k].y << 16) + __uint_as_float(bv[k].y << 16);
;       float o3 = __uint_as_float(av[k].y & 0xffff0000u) + __uint_as_float(bv[k].y & 0xffff0000u);
;       float ss = o0 * o0 + o1 * o1 + o2 * o2 + o3 * o3;
;       ss += shx(ss, 1, lane); ss += shx(ss, 2, lane); ss += shx(ss, 4, lane); ss += shx(ss, 8, lane);
;       float r = rsqrtf(ss * (1.f / 64.f) + 1e-6f);
;       uint2 zz = zv[k];
;       float z0 = bf2f((u16)(zz.x & 0xffff)), z1 = bf2f((u16)(zz.x >> 16)), z2 = bf2f((u16)(zz.y & 0xffff)),
;             z3 = bf2f((u16)(zz.y >> 16));
;       float y0 = o0 * r * w.x * siluf_(z0), y1 = o1 * r * w.y * siluf_(z1), y2 = o2 * r * w.z * siluf_(z2),
;             y3 = o3 * r * w.w * siluf_(z3);
;       if (gidx < ngroups) {
;         int tok = gidx / 6, h = gidx % 6;
;         *(uint2*)(MIX + (size_t)tok * 1024 + 256 + h * 64 + sub * 4) = make_uint2(pack2(y0, y1), pack2(y2, y3));
;       }
.LBB0_517:
	s_or_b64 exec, exec, s[38:39]
	s_waitcnt vmcnt(2)
	v_lshlrev_b32_e32 v50, 16, v32
	s_waitcnt vmcnt(1)
	v_lshlrev_b32_e32 v52, 16, v34
	v_and_b32_e32 v51, 0xffff0000, v32
	v_and_b32_e32 v53, 0xffff0000, v34
	v_lshlrev_b32_e32 v32, 16, v33
	v_lshlrev_b32_e32 v34, 16, v35
	v_and_b32_e32 v33, 0xffff0000, v33
	v_and_b32_e32 v35, 0xffff0000, v35
	v_pk_add_f32 v[50:51], v[50:51], v[52:53]
	v_pk_add_f32 v[32:33], v[32:33], v[34:35]
	v_pk_mul_f32 v[52:53], v[50:51], v[50:51]
	v_pk_mul_f32 v[34:35], v[32:33], v[32:33]
	v_add_f32_e32 v21, v52, v53
	v_add_f32_e32 v21, v21, v34
	v_add_f32_e32 v21, v35, v21
	s_nop 1
	v_mov_b32_dpp v34, v21 quad_perm:[1,0,3,2] row_mask:0xf bank_mask:0xf
	s_waitcnt vmcnt(0)
	v_and_b32_e32 v55, 0xffff0000, v31
	v_lshlrev_b32_e32 v54, 16, v31
	v_mul_f32_e32 v35, 0xbfb8aa3b, v55
	v_exp_f32_e32 v35, v35
	s_waitcnt lgkmcnt(0)
	v_add_f32_e32 v21, v21, v34
	s_nop 1
	v_mov_b32_dpp v52, v21 quad_perm:[2,3,0,1] row_mask:0xf bank_mask:0xf
	v_mul_f32_e32 v49, 0xbfb8aa3b, v54
	v_exp_f32_e32 v49, v49
	v_add_f32_e32 v34, 1.0, v35
	v_rcp_f32_e32 v35, v34
	s_waitcnt lgkmcnt(0)
	v_add_f32_e32 v21, v21, v52
	v_add_f32_e32 v34, 1.0, v49
	s_nop 1
	v_mov_b32_dpp v49, v21 row_half_mirror row_mask:0xf bank_mask:0xf
	v_and_b32_e32 v31, 0xffff0000, v30
	v_lshlrev_b32_e32 v30, 16, v30
	v_mul_f32_e32 v52, 0xbfb8aa3b, v31
	v_exp_f32_e32 v52, v52
	s_waitcnt lgkmcnt(0)
	v_add_f32_e32 v21, v21, v49
	s_nop 1
	v_mov_b32_dpp v49, v21 row_mirror row_mask:0xf bank_mask:0xf
	v_mul_f32_e32 v53, 0xbfb8aa3b, v30
	v_exp_f32_e32 v56, v53
	v_add_f32_e32 v52, 1.0, v52
	v_rcp_f32_e32 v53, v52
	s_waitcnt lgkmcnt(0)
	v_add_f32_e32 v21, v21, v49
	v_fmamk_f32 v21, v21, 0x3c800000, v177
	v_mul_f32_e32 v49, 0x4b800000, v21
	v_cmp_gt_f32_e32 vcc, s15, v21
	v_add_f32_e32 v52, 1.0, v56
	v_rcp_f32_e32 v52, v52
	v_cndmask_b32_e32 v21, v21, v49, vcc
	v_rsq_f32_e32 v49, v21
	v_rcp_f32_e32 v34, v34
	v_pk_mul_f32 v[52:53], v[52:53], v[30:31]
	v_lshlrev_b32_e32 v56, 16, v28
	v_mul_f32_e32 v30, 0x45800000, v49
	v_pk_mul_f32 v[34:35], v[34:35], v[54:55]
	v_cndmask_b32_e32 v54, v49, v30, vcc
	v_lshlrev_b32_e32 v30, 16, v26
	v_and_b32_e32 v31, 0xffff0000, v26
	v_and_b32_e32 v57, 0xffff0000, v28
	v_pk_add_f32 v[30:31], v[30:31], v[56:57]
	v_lshlrev_b32_e32 v26, 16, v27
	v_lshlrev_b32_e32 v28, 16, v29
	v_and_b32_e32 v27, 0xffff0000, v27
	v_and_b32_e32 v29, 0xffff0000, v29
	v_pk_add_f32 v[26:27], v[26:27], v[28:29]
	v_pk_mul_f32 v[28:29], v[30:31], v[30:31]
	v_pk_mul_f32 v[56:57], v[26:27], v[26:27]
	v_add_f32_e32 v28, v28, v29
	v_add_f32_e32 v28, v28, v56
	v_add_f32_e32 v49, v57, v28
	s_nop 1
	v_mov_b32_dpp v55, v49 quad_perm:[1,0,3,2] row_mask:0xf bank_mask:0xf
	v_ashrrev_i32_e32 v21, 31, v20
	v_lshlrev_b64 v[20:21], 11, v[20:21]
	v_lshl_add_u64 v[20:21], s[48:49], 0, v[20:21]
	v_lshl_add_u64 v[20:21], v[22:23], 1, v[20:21]
	s_waitcnt lgkmcnt(0)
	v_pk_mul_f32 v[28:29], v[32:33], v[54:55] op_sel_hi:[1,0]
	v_pk_mul_f32 v[32:33], v[50:51], v[54:55] op_sel_hi:[1,0]
	v_pk_mul_f32 v[28:29], v[4:5], v[28:29]
	v_pk_mul_f32 v[32:33], v[2:3], v[32:33]
	v_pk_mul_f32 v[28:29], v[34:35], v[28:29]
	v_add_f32_e32 v34, v49, v55
	s_nop 1
	v_mov_b32_dpp v35, v34 quad_perm:[2,3,0,1] row_mask:0xf bank_mask:0xf
	v_pk_mul_f32 v[32:33], v[52:53], v[32:33]
	v_lshl_add_u64 v[22:23], v[20:21], 0, v[0:1]
	v_cvt_pk_bf16_f32 v32, v32, v33
	v_cvt_pk_bf16_f32 v33, v28, v29
	s_waitcnt lgkmcnt(0)
	v_add_f32_e32 v28, v34, v35
	s_nop 1
	v_mov_b32_dpp v29, v28 row_half_mirror row_mask:0xf bank_mask:0xf
	s_mov_b32 s38, 0x1f64e000
	v_add_co_u32_e32 v22, vcc, s38, v22
	s_waitcnt lgkmcnt(0)
	v_add_f32_e32 v20, v28, v29
	s_nop 1
	v_mov_b32_dpp v21, v20 row_mirror row_mask:0xf bank_mask:0xf
	v_addc_co_u32_e32 v23, vcc, 0, v23, vcc
	global_store_dwordx2 v[22:23], v[32:33], off offset:768
	s_and_saveexec_b64 s[38:39], s[4:5]
	s_cbranch_execz .LBB0_519
	s_waitcnt lgkmcnt(0)
	v_add_f32_e32 v20, v20, v21
	v_fmamk_f32 v20, v20, 0x3c800000, v177
	v_cmp_gt_f32_e32 vcc, s15, v20
	v_mul_f32_e32 v21, 0x4b800000, v20
	v_and_b32_e32 v23, 0xffff0000, v25
	v_cndmask_b32_e32 v20, v20, v21, vcc
	v_rsq_f32_e32 v20, v20
	v_lshlrev_b32_e32 v22, 16, v25
	v_and_b32_e32 v25, 0xffff0000, v24
	v_lshlrev_b32_e32 v24, 16, v24
	v_mul_f32_e32 v21, 0x45800000, v20
	v_cndmask_b32_e32 v20, v20, v21, vcc
	v_mul_f32_e32 v21, 0xbfb8aa3b, v23
	v_exp_f32_e32 v21, v21
	s_nop 0
	v_add_f32_e32 v21, 1.0, v21
	v_rcp_f32_e32 v29, v21
	v_mul_f32_e32 v21, 0xbfb8aa3b, v22
	v_exp_f32_e32 v21, v21
	s_nop 0
	v_add_f32_e32 v21, 1.0, v21
	v_rcp_f32_e32 v28, v21
	v_pk_mul_f32 v[26:27], v[26:27], v[20:21] op_sel_hi:[1,0]
	v_mul_f32_e32 v21, 0xbfb8aa3b, v25
	v_exp_f32_e32 v21, v21
	v_pk_mul_f32 v[22:23], v[28:29], v[22:23]
	v_pk_mul_f32 v[26:27], v[4:5], v[26:27]
	v_add_f32_e32 v21, 1.0, v21
	v_pk_mul_f32 v[22:23], v[22:23], v[26:27]
	v_rcp_f32_e32 v27, v21
	v_mul_f32_e32 v21, 0xbfb8aa3b, v24
	v_exp_f32_e32 v21, v21
	s_nop 0
	v_add_f32_e32 v21, 1.0, v21
	v_rcp_f32_e32 v26, v21
	v_pk_mul_f32 v[20:21], v[30:31], v[20:21] op_sel_hi:[1,0]
	v_pk_mul_f32 v[24:25], v[26:27], v[24:25]
	v_pk_mul_f32 v[20:21], v[2:3], v[20:21]
	s_nop 0
	v_pk_mul_f32 v[20:21], v[24:25], v[20:21]
	v_add_u32_e32 v24, v47, v48
	v_mul_lo_u32 v25, v24, 6
	v_sub_u32_e32 v26, v46, v25
	v_ashrrev_i32_e32 v25, 31, v24
	v_cvt_pk_bf16_f32 v20, v20, v21
	v_cvt_pk_bf16_f32 v21, v22, v23
	v_lshlrev_b64 v[22:23], 11, v[24:25]
	v_lshlrev_b32_e32 v24, 6, v26
	v_lshl_add_u64 v[22:23], s[48:49], 0, v[22:23]
	v_ashrrev_i32_e32 v25, 31, v24
	v_lshl_add_u64 v[22:23], v[24:25], 1, v[22:23]
	v_lshl_add_u64 v[22:23], v[22:23], 0, v[0:1]
	v_add_co_u32_e32 v22, vcc, 0x1f64e000, v22
	s_nop 1
	v_addc_co_u32_e32 v23, vcc, 0, v23, vcc
	global_store_dwordx2 v[22:23], v[20:21], off offset:768
; __device__ __forceinline__ float bf2f(u16 h) { return __uint_as_float(((unsigned)h) << 16); }
; __device__ __forceinline__ float siluf_(float x) { return x * __builtin_amdgcn_rcpf(1.f + __expf(-x)); }
; __device__ void phase_bnorm(const Params& p, int l, int wv) {
;     ...
;     for (int k = 0; k < 4; ++k) {
;       int gidx = g0 + k * gstride;
;       float o0 = __uint_as_float(av[k].x << 16) + __uint_as_float(bv[k].x << 16);
;       float o1 = __uint_as_float(av[k].x & 0xffff0000u) + __uint_as_float(bv[k].x & 0xffff0000u);
;       float o2 = __uint_as_float(av[k].y << 16) + __uint_as_float(bv[k].y << 16);
;       float o3 = __uint_as_float(av[k].y & 0xffff0000u) + __uint_as_float(bv[k].y & 0xffff0000u);
;       float ss = o0 * o0 + o1 * o1 + o2 * o2 + o3 * o3;
;       ss += shx(ss, 1, lane); ss += shx(ss, 2, lane); ss += shx(ss, 4, lane); ss += shx(ss, 8, lane);
;       float r = rsqrtf(ss * (1.f / 64.f) + 1e-6f);
;       uint2 zz = zv[k];
;       float z0 = bf2f((u16)(zz.x & 0xffff)), z1 = bf2f((u16)(zz.x >> 16)), z2 = bf2f((u16)(zz.y & 0xffff)),
;             z3 = bf2f((u16)(zz.y >> 16));
;       float y0 = o0 * r * w.x * siluf_(z0), y1 = o1 * r * w.y * siluf_(z1), y2 = o2 * r * w.z * siluf_(z2),
;             y3 = o3 * r * w.w * siluf_(z3);
;       if (gidx < ngroups) {
;         int tok = gidx / 6, h = gidx % 6;
;         *(uint2*)(MIX + (size_t)tok * 1024 + 256 + h * 64 + sub * 4) = make_uint2(pack2(y0, y1), pack2(y2, y3));
;       }
.LBB0_519:
	s_or_b64 exec, exec, s[38:39]
	v_lshlrev_b32_e32 v20, 16, v14
	v_lshlrev_b32_e32 v22, 16, v18
	s_waitcnt lgkmcnt(0)
	v_and_b32_e32 v21, 0xffff0000, v14
	v_and_b32_e32 v23, 0xffff0000, v18
	v_pk_add_f32 v[20:21], v[20:21], v[22:23]
	v_lshlrev_b32_e32 v14, 16, v15
	v_lshlrev_b32_e32 v18, 16, v19
	v_and_b32_e32 v15, 0xffff0000, v15
	v_and_b32_e32 v19, 0xffff0000, v19
	v_pk_add_f32 v[14:15], v[14:15], v[18:19]
	v_pk_mul_f32 v[18:19], v[20:21], v[20:21]
	v_pk_mul_f32 v[22:23], v[14:15], v[14:15]
	v_add_f32_e32 v18, v18, v19
	v_add_f32_e32 v18, v18, v22
	v_add_f32_e32 v18, v23, v18
	s_nop 1
	v_mov_b32_dpp v19, v18 quad_perm:[1,0,3,2] row_mask:0xf bank_mask:0xf
	s_waitcnt lgkmcnt(0)
	v_add_f32_e32 v18, v18, v19
	s_nop 1
	v_mov_b32_dpp v19, v18 quad_perm:[2,3,0,1] row_mask:0xf bank_mask:0xf
	s_waitcnt lgkmcnt(0)
	v_add_f32_e32 v18, v18, v19
	s_nop 1
	v_mov_b32_dpp v19, v18 row_half_mirror row_mask:0xf bank_mask:0xf
	s_waitcnt lgkmcnt(0)
	v_add_f32_e32 v18, v18, v19
	s_nop 1
	v_mov_b32_dpp v19, v18 row_mirror row_mask:0xf bank_mask:0xf
	s_and_saveexec_b64 s[4:5], s[2:3]
	s_cbranch_execz .LBB0_521
	s_waitcnt lgkmcnt(0)
	v_add_f32_e32 v18, v18, v19
	v_fmamk_f32 v18, v18, 0x3c800000, v177
	v_cmp_gt_f32_e32 vcc, s15, v18
	v_mul_f32_e32 v19, 0x4b800000, v18
	v_and_b32_e32 v23, 0xffff0000, v17
	v_cndmask_b32_e32 v18, v18, v19, vcc
	v_rsq_f32_e32 v18, v18
	v_lshlrev_b32_e32 v22, 16, v17
	v_and_b32_e32 v17, 0xffff0000, v16
	v_lshlrev_b32_e32 v16, 16, v16
	v_mul_f32_e32 v19, 0x45800000, v18
	v_cndmask_b32_e32 v18, v18, v19, vcc
	v_mul_f32_e32 v19, 0xbfb8aa3b, v23
	v_exp_f32_e32 v19, v19
	s_nop 0
	v_add_f32_e32 v19, 1.0, v19
	v_rcp_f32_e32 v25, v19
	v_mul_f32_e32 v19, 0xbfb8aa3b, v22
	v_exp_f32_e32 v19, v19
	s_nop 0
	v_add_f32_e32 v19, 1.0, v19
	v_rcp_f32_e32 v24, v19
	v_pk_mul_f32 v[14:15], v[14:15], v[18:19] op_sel_hi:[1,0]
	v_mul_f32_e32 v19, 0xbfb8aa3b, v17
	v_exp_f32_e32 v19, v19
	v_pk_mul_f32 v[22:23], v[24:25], v[22:23]
	v_pk_mul_f32 v[14:15], v[4:5], v[14:15]
	v_add_f32_e32 v19, 1.0, v19
	v_pk_mul_f32 v[14:15], v[22:23], v[14:15]
	v_rcp_f32_e32 v23, v19
	v_mul_f32_e32 v19, 0xbfb8aa3b, v16
	v_exp_f32_e32 v19, v19
	s_nop 0
	v_add_f32_e32 v19, 1.0, v19
	v_rcp_f32_e32 v22, v19
	v_pk_mul_f32 v[18:19], v[20:21], v[18:19] op_sel_hi:[1,0]
	v_pk_mul_f32 v[16:17], v[22:23], v[16:17]
	v_pk_mul_f32 v[18:19], v[2:3], v[18:19]
	s_nop 0
	v_pk_mul_f32 v[16:17], v[16:17], v[18:19]
	v_add_u32_e32 v18, v44, v45
	v_mul_lo_u32 v19, v18, 6
	v_sub_u32_e32 v20, v43, v19
	v_ashrrev_i32_e32 v19, 31, v18
	v_cvt_pk_bf16_f32 v16, v16, v17
	v_cvt_pk_bf16_f32 v17, v14, v15
	v_lshlrev_b64 v[14:15], 11, v[18:19]
	v_lshlrev_b32_e32 v18, 6, v20
	v_lshl_add_u64 v[14:15], s[48:49], 0, v[14:15]
	v_ashrrev_i32_e32 v19, 31, v18
	v_lshl_add_u64 v[14:15], v[18:19], 1, v[14:15]
	v_lshl_add_u64 v[14:15], v[14:15], 0, v[0:1]
	v_add_co_u32_e32 v14, vcc, 0x1f64e000, v14
	s_nop 1
	v_addc_co_u32_e32 v15, vcc, 0, v15, vcc
	global_store_dwordx2 v[14:15], v[16:17], off offset:768
.LBB0_521:
	s_or_b64 exec, exec, s[4:5]
	v_lshlrev_b32_e32 v14, 16, v10
	v_lshlrev_b32_e32 v16, 16, v12
	v_and_b32_e32 v15, 0xffff0000, v10
	v_and_b32_e32 v17, 0xffff0000, v12
	v_pk_add_f32 v[14:15], v[14:15], v[16:17]
	v_lshlrev_b32_e32 v10, 16, v11
	v_lshlrev_b32_e32 v12, 16, v13
	v_and_b32_e32 v11, 0xffff0000, v11
	v_and_b32_e32 v13, 0xffff0000, v13
	v_pk_add_f32 v[10:11], v[10:11], v[12:13]
	v_pk_mul_f32 v[12:13], v[14:15], v[14:15]
	v_pk_mul_f32 v[16:17], v[10:11], v[10:11]
	v_add_f32_e32 v12, v12, v13
	v_add_f32_e32 v12, v12, v16
	v_add_f32_e32 v12, v17, v12
	s_nop 1
	v_mov_b32_dpp v13, v12 quad_perm:[1,0,3,2] row_mask:0xf bank_mask:0xf
	s_waitcnt lgkmcnt(0)
	v_add_f32_e32 v12, v12, v13
	s_nop 1
	v_mov_b32_dpp v13, v12 quad_perm:[2,3,0,1] row_mask:0xf bank_mask:0xf
	s_waitcnt lgkmcnt(0)
	v_add_f32_e32 v12, v12, v13
	s_nop 1
	v_mov_b32_dpp v13, v12 row_half_mirror row_mask:0xf bank_mask:0xf
	s_waitcnt lgkmcnt(0)
	v_add_f32_e32 v12, v12, v13
	s_nop 1
	v_mov_b32_dpp v13, v12 row_mirror row_mask:0xf bank_mask:0xf
	s_and_saveexec_b64 s[2:3], s[0:1]
	s_cbranch_execz .LBB0_510
	s_waitcnt lgkmcnt(0)
	v_add_f32_e32 v12, v12, v13
	v_fmamk_f32 v12, v12, 0x3c800000, v177
	v_cmp_gt_f32_e32 vcc, s15, v12
	v_mul_f32_e32 v13, 0x4b800000, v12
	v_and_b32_e32 v17, 0xffff0000, v9
	v_cndmask_b32_e32 v12, v12, v13, vcc
	v_rsq_f32_e32 v12, v12
	v_lshlrev_b32_e32 v16, 16, v9
	v_and_b32_e32 v9, 0xffff0000, v8
	v_lshlrev_b32_e32 v8, 16, v8
	v_mul_f32_e32 v13, 0x45800000, v12
	v_cndmask_b32_e32 v12, v12, v13, vcc
	v_mul_f32_e32 v13, 0xbfb8aa3b, v17
	v_exp_f32_e32 v13, v13
	s_nop 0
	v_add_f32_e32 v13, 1.0, v13
	v_rcp_f32_e32 v19, v13
	v_mul_f32_e32 v13, 0xbfb8aa3b, v16
	v_exp_f32_e32 v13, v13
	s_nop 0
	v_add_f32_e32 v13, 1.0, v13
	v_rcp_f32_e32 v18, v13
	v_pk_mul_f32 v[10:11], v[10:11], v[12:13] op_sel_hi:[1,0]
	v_mul_f32_e32 v13, 0xbfb8aa3b, v9
	v_exp_f32_e32 v13, v13
	v_pk_mul_f32 v[16:17], v[18:19], v[16:17]
	v_pk_mul_f32 v[10:11], v[4:5], v[10:11]
	v_add_f32_e32 v13, 1.0, v13
	v_pk_mul_f32 v[10:11], v[16:17], v[10:11]
	v_rcp_f32_e32 v17, v13
	v_mul_f32_e32 v13, 0xbfb8aa3b, v8
	v_exp_f32_e32 v13, v13
	s_nop 0
	v_add_f32_e32 v13, 1.0, v13
	v_rcp_f32_e32 v16, v13
	v_pk_mul_f32 v[12:13], v[14:15], v[12:13] op_sel_hi:[1,0]
	v_pk_mul_f32 v[8:9], v[16:17], v[8:9]
	v_pk_mul_f32 v[12:13], v[2:3], v[12:13]
	s_nop 0
	v_pk_mul_f32 v[8:9], v[8:9], v[12:13]
	v_add_u32_e32 v12, v41, v42
	v_mul_lo_u32 v13, v12, 6
	v_sub_u32_e32 v14, v40, v13
	v_ashrrev_i32_e32 v13, 31, v12
	v_cvt_pk_bf16_f32 v8, v8, v9
	v_cvt_pk_bf16_f32 v9, v10, v11
	v_lshlrev_b64 v[10:11], 11, v[12:13]
	v_lshlrev_b32_e32 v12, 6, v14
	v_lshl_add_u64 v[10:11], s[48:49], 0, v[10:11]
	v_ashrrev_i32_e32 v13, 31, v12
	v_lshl_add_u64 v[10:11], v[12:13], 1, v[10:11]
	v_lshl_add_u64 v[10:11], v[10:11], 0, v[0:1]
	v_add_co_u32_e32 v10, vcc, 0x1f64e000, v10
	s_nop 1
	v_addc_co_u32_e32 v11, vcc, 0, v11, vcc
	global_store_dwordx2 v[10:11], v[8:9], off offset:768
	s_branch .LBB0_510
